# FoX gate logits: separate 64x32 mini-GEMM per WG instead of a padded 25th column tile (drops the 7th round)
# speedup vs baseline: 1.0051x; 1.0051x over previous
; __global__ void __launch_bounds__(NWAVES * 64, 2) mega_fwd(Args a) {
;     ...
;             if (st == 0) { aoff = WS_XN; ooff = WS_QKV; K = DM; mode = 0;
;                 if (!fox) { boff = WS_WSI + (size_t)j * N_SWA_IN * DM * 2; N = N_SWA_IN; ldc = N_SWA_IN; }
;                 else { boff = WS_WFI + (size_t)j * N_FOX_PAD * DM * 2; N = N_FOX_PAD; ldc = N_FOX_MAIN; ntm = N_FOX_MAIN / 256; } }
;             else if (st == 3) { aoff = WS_AO; boff = (fox ? WS_WFO : WS_WSO) + (size_t)j * DM * DM * 2; ooff = WS_Y; N = DM; K = DM; mode = 1; ldc = DM; }
;             else if (st == 5) { aoff = WS_XN; boff = WS_WGU + (size_t)layer * N_GU * DM * 2; ooff = WS_HB; N = N_GU; K = DM; mode = 2; ldc = DFF; }
;             else { aoff = WS_HB; boff = WS_WDN + (size_t)layer * DM * DFF * 2; ooff = WS_Y; N = DM; K = DFF; mode = 1; ldc = DM; }
;             pg8::Gemm gm{(const bf16*)(ws + aoff), (const bf16*)(ws + boff), M, N, K}; pg8::StaticOrder S; S.init(M, N, G, bx);
;             pg8::EpiAny E{mode, true, ws + ooff, ldc, ntm, (float*)(ws + ((st == 0 && !fox) ? WS_ROPE : WS_GATE))};
.LBB0_304:
	s_andn2_b64 vcc, exec, s[8:9]
	s_cbranch_vccnz .LBB0_306
	s_mul_i32 s0, s56, 0xc00000
	s_add_i32 s6, s0, 0x800000
	s_mul_i32 s0, s56, 0x1900000
	s_add_i32 s7, s0, 0x3000000
	s_and_b64 s[0:1], s[4:5], exec
	s_movk_i32 s0, 0x1800
	s_cselect_b32 s84, 0xc00, s0
	s_cselect_b32 s22, 2.0, 24
	s_cselect_b32 s54, 12, 24
	s_cselect_b32 s14, s6, s7
	s_mov_b32 s15, s85
	s_mov_b64 s[6:7], -1
	s_mov_b64 s[44:45], s[84:85]

;     __device__ __forceinline__ void operator()(const f32x4 (&acc)[2][2][4][2], const Unit& u, int wr, int wc, int fr, int fq) const {
;     ...
;         } else if (wc == 0) {
; #pragma unroll
;             for (int ai = 0; ai < 2; ++ai)
; #pragma unroll
;                 for (int m = 0; m < 4; ++m) { float* gp = G + (size_t)(row0 + ai * HALF + m * 16) * 32 + 8 * fq;
;                     *(f32x4*)gp = acc[ai][0][m][0]; *(f32x4*)(gp + 4) = acc[ai][0][m][1]; }
;         }
.LBB0_422:
	s_and_b32 s4, s33, 15
	s_cmp_lg_u32 s4, 8
	s_cbranch_scc1 .Lgate_skip
	v_readfirstlane_b32 s4, v147
	v_and_b32_e32 v130, 63, v147
	s_lshr_b32 s4, s4, 6
	s_lshl_b32 s5, s4, 9
	s_lshr_b32 s6, s33, 4
	s_mul_i32 s6, s6, 0x1900000
	s_add_u32 s6, s6, 0x4800000
	s_add_u32 s6, s6, s5
	s_add_u32 s8, s60, s6
	s_addc_u32 s9, s61, 0
	v_and_b32_e32 v131, 15, v130
	v_lshrrev_b32_e32 v132, 4, v130
	v_lshlrev_b32_e32 v133, 12, v131
	v_lshl_add_u32 v134, v132, 4, v133
	v_add_u32_e32 v135, 0x10000, v134
	v_add_u32_e32 v136, 0x20000, v134
	v_add_u32_e32 v137, 0x30000, v134
	v_lshlrev_b32_e32 v138, 4, v130
	s_lshl_b32 s7, s4, 13
	v_add_u32_e32 v139, s7, v138
	s_lshl_b32 s7, s4, 10
	v_add_u32_e32 v140, s7, v138
	v_lshlrev_b32_e32 v141, 7, v131
	v_lshl_add_u32 v141, v132, 4, v141
	s_mov_b32 s12, s2
.Lgate_loop:
	s_lshl_b32 s6, s12, 18
	s_add_u32 s6, s6, s5
	s_add_u32 s6, s6, 0x17a00000
	s_add_u32 s16, s60, s6
	s_addc_u32 s17, s61, 0
	v_mov_b32_e32 v2, 0
	v_mov_b32_e32 v3, 0
	v_mov_b32_e32 v4, 0
	v_mov_b32_e32 v5, 0
	v_mov_b32_e32 v6, 0
	v_mov_b32_e32 v7, 0
	v_mov_b32_e32 v8, 0
	v_mov_b32_e32 v9, 0
	v_mov_b32_e32 v10, 0
	v_mov_b32_e32 v11, 0
	v_mov_b32_e32 v12, 0
	v_mov_b32_e32 v13, 0
	v_mov_b32_e32 v14, 0
	v_mov_b32_e32 v15, 0
	v_mov_b32_e32 v16, 0
	v_mov_b32_e32 v17, 0
	v_mov_b32_e32 v18, 0
	v_mov_b32_e32 v19, 0
	v_mov_b32_e32 v20, 0
	v_mov_b32_e32 v21, 0
	v_mov_b32_e32 v22, 0
	v_mov_b32_e32 v23, 0
	v_mov_b32_e32 v24, 0
	v_mov_b32_e32 v25, 0
	v_mov_b32_e32 v26, 0
	v_mov_b32_e32 v27, 0
	v_mov_b32_e32 v28, 0
	v_mov_b32_e32 v29, 0
	v_mov_b32_e32 v30, 0
	v_mov_b32_e32 v31, 0
	v_mov_b32_e32 v32, 0
	v_mov_b32_e32 v33, 0
	global_load_dwordx4 v[34:37], v134, s[16:17] offset:0
	global_load_dwordx4 v[38:41], v135, s[16:17] offset:0
	global_load_dwordx4 v[42:45], v136, s[16:17] offset:0
	global_load_dwordx4 v[46:49], v137, s[16:17] offset:0
	global_load_dwordx4 v[50:53], v134, s[8:9] offset:0
	global_load_dwordx4 v[54:57], v135, s[8:9] offset:0
	global_load_dwordx4 v[58:61], v134, s[16:17] offset:64
	global_load_dwordx4 v[62:65], v135, s[16:17] offset:64
	global_load_dwordx4 v[66:69], v136, s[16:17] offset:64
	global_load_dwordx4 v[70:73], v137, s[16:17] offset:64
	global_load_dwordx4 v[74:77], v134, s[8:9] offset:64
	global_load_dwordx4 v[78:81], v135, s[8:9] offset:64
	global_load_dwordx4 v[82:85], v134, s[16:17] offset:128
	global_load_dwordx4 v[86:89], v135, s[16:17] offset:128
	global_load_dwordx4 v[90:93], v136, s[16:17] offset:128
	global_load_dwordx4 v[94:97], v137, s[16:17] offset:128
	global_load_dwordx4 v[98:101], v134, s[8:9] offset:128
	global_load_dwordx4 v[102:105], v135, s[8:9] offset:128
	global_load_dwordx4 v[106:109], v134, s[16:17] offset:192
	global_load_dwordx4 v[110:113], v135, s[16:17] offset:192
	global_load_dwordx4 v[114:117], v136, s[16:17] offset:192
	global_load_dwordx4 v[118:121], v137, s[16:17] offset:192
	global_load_dwordx4 v[122:125], v134, s[8:9] offset:192
	global_load_dwordx4 v[126:129], v135, s[8:9] offset:192
	s_waitcnt vmcnt(18)
	v_mfma_f32_16x16x32_bf16 v[2:5], v[50:53], v[34:37], v[2:5]
	v_mfma_f32_16x16x32_bf16 v[6:9], v[54:57], v[34:37], v[6:9]
	v_mfma_f32_16x16x32_bf16 v[10:13], v[50:53], v[38:41], v[10:13]
	v_mfma_f32_16x16x32_bf16 v[14:17], v[54:57], v[38:41], v[14:17]
	v_mfma_f32_16x16x32_bf16 v[18:21], v[50:53], v[42:45], v[18:21]
	v_mfma_f32_16x16x32_bf16 v[22:25], v[54:57], v[42:45], v[22:25]
	v_mfma_f32_16x16x32_bf16 v[26:29], v[50:53], v[46:49], v[26:29]
	v_mfma_f32_16x16x32_bf16 v[30:33], v[54:57], v[46:49], v[30:33]
	global_load_dwordx4 v[34:37], v134, s[16:17] offset:256
	global_load_dwordx4 v[38:41], v135, s[16:17] offset:256
	global_load_dwordx4 v[42:45], v136, s[16:17] offset:256
	global_load_dwordx4 v[46:49], v137, s[16:17] offset:256
	global_load_dwordx4 v[50:53], v134, s[8:9] offset:256
	global_load_dwordx4 v[54:57], v135, s[8:9] offset:256
	s_waitcnt vmcnt(18)
	v_mfma_f32_16x16x32_bf16 v[2:5], v[74:77], v[58:61], v[2:5]
	v_mfma_f32_16x16x32_bf16 v[6:9], v[78:81], v[58:61], v[6:9]
	v_mfma_f32_16x16x32_bf16 v[10:13], v[74:77], v[62:65], v[10:13]
	v_mfma_f32_16x16x32_bf16 v[14:17], v[78:81], v[62:65], v[14:17]
	v_mfma_f32_16x16x32_bf16 v[18:21], v[74:77], v[66:69], v[18:21]
	v_mfma_f32_16x16x32_bf16 v[22:25], v[78:81], v[66:69], v[22:25]
	v_mfma_f32_16x16x32_bf16 v[26:29], v[74:77], v[70:73], v[26:29]
	v_mfma_f32_16x16x32_bf16 v[30:33], v[78:81], v[70:73], v[30:33]
	global_load_dwordx4 v[58:61], v134, s[16:17] offset:320
	global_load_dwordx4 v[62:65], v135, s[16:17] offset:320
	global_load_dwordx4 v[66:69], v136, s[16:17] offset:320
	global_load_dwordx4 v[70:73], v137, s[16:17] offset:320
	global_load_dwordx4 v[74:77], v134, s[8:9] offset:320
	global_load_dwordx4 v[78:81], v135, s[8:9] offset:320
	s_waitcnt vmcnt(18)
	v_mfma_f32_16x16x32_bf16 v[2:5], v[98:101], v[82:85], v[2:5]
	v_mfma_f32_16x16x32_bf16 v[6:9], v[102:105], v[82:85], v[6:9]
	v_mfma_f32_16x16x32_bf16 v[10:13], v[98:101], v[86:89], v[10:13]
	v_mfma_f32_16x16x32_bf16 v[14:17], v[102:105], v[86:89], v[14:17]
	v_mfma_f32_16x16x32_bf16 v[18:21], v[98:101], v[90:93], v[18:21]
	v_mfma_f32_16x16x32_bf16 v[22:25], v[102:105], v[90:93], v[22:25]
	v_mfma_f32_16x16x32_bf16 v[26:29], v[98:101], v[94:97], v[26:29]
	v_mfma_f32_16x16x32_bf16 v[30:33], v[102:105], v[94:97], v[30:33]
	global_load_dwordx4 v[82:85], v134, s[16:17] offset:384
	global_load_dwordx4 v[86:89], v135, s[16:17] offset:384
	global_load_dwordx4 v[90:93], v136, s[16:17] offset:384
	global_load_dwordx4 v[94:97], v137, s[16:17] offset:384
	global_load_dwordx4 v[98:101], v134, s[8:9] offset:384
	global_load_dwordx4 v[102:105], v135, s[8:9] offset:384
	s_waitcnt vmcnt(18)
;     __device__ __forceinline__ void operator()(const f32x4 (&acc)[2][2][4][2], const Unit& u, int wr, int wc, int fr, int fq) const {
;     ...
;         } else if (wc == 0) {
; #pragma unroll
;             for (int ai = 0; ai < 2; ++ai)
; #pragma unroll
;                 for (int m = 0; m < 4; ++m) { float* gp = G + (size_t)(row0 + ai * HALF + m * 16) * 32 + 8 * fq;
;                     *(f32x4*)gp = acc[ai][0][m][0]; *(f32x4*)(gp + 4) = acc[ai][0][m][1]; }
;         }
	v_mfma_f32_16x16x32_bf16 v[2:5], v[122:125], v[106:109], v[2:5]
	v_mfma_f32_16x16x32_bf16 v[6:9], v[126:129], v[106:109], v[6:9]
	v_mfma_f32_16x16x32_bf16 v[10:13], v[122:125], v[110:113], v[10:13]
	v_mfma_f32_16x16x32_bf16 v[14:17], v[126:129], v[110:113], v[14:17]
	v_mfma_f32_16x16x32_bf16 v[18:21], v[122:125], v[114:117], v[18:21]
	v_mfma_f32_16x16x32_bf16 v[22:25], v[126:129], v[114:117], v[22:25]
	v_mfma_f32_16x16x32_bf16 v[26:29], v[122:125], v[118:121], v[26:29]
	v_mfma_f32_16x16x32_bf16 v[30:33], v[126:129], v[118:121], v[30:33]
	global_load_dwordx4 v[106:109], v134, s[16:17] offset:448
	global_load_dwordx4 v[110:113], v135, s[16:17] offset:448
	global_load_dwordx4 v[114:117], v136, s[16:17] offset:448
	global_load_dwordx4 v[118:121], v137, s[16:17] offset:448
	global_load_dwordx4 v[122:125], v134, s[8:9] offset:448
	global_load_dwordx4 v[126:129], v135, s[8:9] offset:448
	s_waitcnt vmcnt(18)
	v_mfma_f32_16x16x32_bf16 v[2:5], v[50:53], v[34:37], v[2:5]
	v_mfma_f32_16x16x32_bf16 v[6:9], v[54:57], v[34:37], v[6:9]
	v_mfma_f32_16x16x32_bf16 v[10:13], v[50:53], v[38:41], v[10:13]
	v_mfma_f32_16x16x32_bf16 v[14:17], v[54:57], v[38:41], v[14:17]
	v_mfma_f32_16x16x32_bf16 v[18:21], v[50:53], v[42:45], v[18:21]
	v_mfma_f32_16x16x32_bf16 v[22:25], v[54:57], v[42:45], v[22:25]
	v_mfma_f32_16x16x32_bf16 v[26:29], v[50:53], v[46:49], v[26:29]
	v_mfma_f32_16x16x32_bf16 v[30:33], v[54:57], v[46:49], v[30:33]
	s_waitcnt vmcnt(12)
	v_mfma_f32_16x16x32_bf16 v[2:5], v[74:77], v[58:61], v[2:5]
	v_mfma_f32_16x16x32_bf16 v[6:9], v[78:81], v[58:61], v[6:9]
	v_mfma_f32_16x16x32_bf16 v[10:13], v[74:77], v[62:65], v[10:13]
	v_mfma_f32_16x16x32_bf16 v[14:17], v[78:81], v[62:65], v[14:17]
	v_mfma_f32_16x16x32_bf16 v[18:21], v[74:77], v[66:69], v[18:21]
	v_mfma_f32_16x16x32_bf16 v[22:25], v[78:81], v[66:69], v[22:25]
	v_mfma_f32_16x16x32_bf16 v[26:29], v[74:77], v[70:73], v[26:29]
	v_mfma_f32_16x16x32_bf16 v[30:33], v[78:81], v[70:73], v[30:33]
	s_waitcnt vmcnt(6)
	v_mfma_f32_16x16x32_bf16 v[2:5], v[98:101], v[82:85], v[2:5]
	v_mfma_f32_16x16x32_bf16 v[6:9], v[102:105], v[82:85], v[6:9]
	v_mfma_f32_16x16x32_bf16 v[10:13], v[98:101], v[86:89], v[10:13]
	v_mfma_f32_16x16x32_bf16 v[14:17], v[102:105], v[86:89], v[14:17]
	v_mfma_f32_16x16x32_bf16 v[18:21], v[98:101], v[90:93], v[18:21]
	v_mfma_f32_16x16x32_bf16 v[22:25], v[102:105], v[90:93], v[22:25]
	v_mfma_f32_16x16x32_bf16 v[26:29], v[98:101], v[94:97], v[26:29]
	v_mfma_f32_16x16x32_bf16 v[30:33], v[102:105], v[94:97], v[30:33]
	s_waitcnt vmcnt(0)
	v_mfma_f32_16x16x32_bf16 v[2:5], v[122:125], v[106:109], v[2:5]
	v_mfma_f32_16x16x32_bf16 v[6:9], v[126:129], v[106:109], v[6:9]
	v_mfma_f32_16x16x32_bf16 v[10:13], v[122:125], v[110:113], v[10:13]
	v_mfma_f32_16x16x32_bf16 v[14:17], v[126:129], v[110:113], v[14:17]
	v_mfma_f32_16x16x32_bf16 v[18:21], v[122:125], v[114:117], v[18:21]
	v_mfma_f32_16x16x32_bf16 v[22:25], v[126:129], v[114:117], v[22:25]
	v_mfma_f32_16x16x32_bf16 v[26:29], v[122:125], v[118:121], v[26:29]
	v_mfma_f32_16x16x32_bf16 v[30:33], v[126:129], v[118:121], v[30:33]
	s_nop 7
	s_nop 7
	ds_write_b128 v139, v[2:5] offset:0
	ds_write_b128 v139, v[6:9] offset:1024
	ds_write_b128 v139, v[10:13] offset:2048
	ds_write_b128 v139, v[14:17] offset:3072
	ds_write_b128 v139, v[18:21] offset:4096
	ds_write_b128 v139, v[22:25] offset:5120
	ds_write_b128 v139, v[26:29] offset:6144
	ds_write_b128 v139, v[30:33] offset:7168
	s_waitcnt lgkmcnt(0)
	s_barrier
	ds_read_b128 v[34:37], v140 offset:0
	ds_read_b128 v[38:41], v140 offset:8192
	ds_read_b128 v[42:45], v140 offset:16384
	ds_read_b128 v[46:49], v140 offset:24576
	ds_read_b128 v[50:53], v140 offset:32768
	ds_read_b128 v[54:57], v140 offset:40960
	ds_read_b128 v[58:61], v140 offset:49152
	ds_read_b128 v[62:65], v140 offset:57344
	s_lshl_b32 s6, s12, 13
	s_lshr_b32 s7, s4, 1
	s_lshl_b32 s7, s7, 11
	s_add_u32 s6, s6, s7
	s_and_b32 s7, s4, 1
	s_lshl_b32 s7, s7, 6
	s_add_u32 s6, s6, s7
	s_add_u32 s6, s6, 0x200000
	s_add_u32 s18, s60, s6
	s_addc_u32 s19, s61, 0
	s_waitcnt lgkmcnt(6)
	v_add_f32_e32 v34, v34, v38
	v_add_f32_e32 v35, v35, v39
	v_add_f32_e32 v36, v36, v40
	v_add_f32_e32 v37, v37, v41
	s_waitcnt lgkmcnt(5)
	v_add_f32_e32 v34, v34, v42
	v_add_f32_e32 v35, v35, v43
	v_add_f32_e32 v36, v36, v44
	v_add_f32_e32 v37, v37, v45
	s_waitcnt lgkmcnt(4)
	v_add_f32_e32 v34, v34, v46
	v_add_f32_e32 v35, v35, v47
	v_add_f32_e32 v36, v36, v48
	v_add_f32_e32 v37, v37, v49
	s_waitcnt lgkmcnt(3)
	v_add_f32_e32 v34, v34, v50
	v_add_f32_e32 v35, v35, v51
	v_add_f32_e32 v36, v36, v52
	v_add_f32_e32 v37, v37, v53
	s_waitcnt lgkmcnt(2)
	v_add_f32_e32 v34, v34, v54
	v_add_f32_e32 v35, v35, v55
	v_add_f32_e32 v36, v36, v56
	v_add_f32_e32 v37, v37, v57
	s_waitcnt lgkmcnt(1)
	v_add_f32_e32 v34, v34, v58
	v_add_f32_e32 v35, v35, v59
	v_add_f32_e32 v36, v36, v60
	v_add_f32_e32 v37, v37, v61
	s_waitcnt lgkmcnt(0)
	v_add_f32_e32 v34, v34, v62
	v_add_f32_e32 v35, v35, v63
	v_add_f32_e32 v36, v36, v64
	v_add_f32_e32 v37, v37, v65
	s_nop 4
	global_store_dwordx4 v141, v[34:37], s[18:19]
	s_add_u32 s12, s12, s58
	s_cmpk_lt_u32 s12, 0x100
	s_cbranch_scc0 .Lgate_skip
	s_barrier
	s_branch .Lgate_loop
